# p3_reduce prompt-row rstd work dealt evenly to all workgroups (was workgroups 0-15 only)
# speedup vs baseline: 1.0512x; 1.0008x over previous
.LBB0_1105:
	v_readlane_b32 s4, v254, 0
	s_nop 0
	s_nop 0
	s_nop 0
	v_lshl_add_u32 v0, v171, 8, s4
	s_movk_i32 s4, 0x2000
	v_cmp_gt_i32_e32 vcc, s4, v0
	s_and_saveexec_b64 s[4:5], vcc
	v_readlane_b32 s16, v254, 50
	v_readlane_b32 s17, v254, 51
	s_cbranch_execz .LBB0_1108
	s_mov_b64 s[12:13], 0
	v_mov_b32_e32 v2, 0x358637bd
	s_movk_i32 s14, 0x1fff
